# indexer keeps query fragments of 12 heads resident in spare VGPRs per work item (LDS re-reads per 256-key iteration drop from 34 to 10)
# speedup vs baseline: 1.0391x; 1.0023x over previous
; #define LAS __attribute__((address_space(3)))
; #define GAS __attribute__((address_space(1)))
; __device__ __forceinline__ unsigned cvt_pk_bf16(float lo, float hi) { unsigned r; asm volatile("v_cvt_pk_bf16_f32 %0, %1, %2" : "=v"(r) : "v"(lo), "v"(hi)); return r; }
; __device__ __forceinline__ float bflo(unsigned w) { return __uint_as_float(w << 16); }
; __device__ __forceinline__ float bfhi(unsigned w) { return __uint_as_float(w & 0xffff0000u); }
; __device__ void indexer_item(LAS unsigned char* lds, const bf16_t* Qi, const bf16_t* Ki, const float* Wi, unsigned* maskout, int qt) {
;     ...
;     float wv[16];
; #pragma unroll
;     for (int i = 0; i < 4; ++i) { const f32x4 w4 = *(const GAS f32x4*)(Wi + (size_t)(t0 + q) * 16 + i * 4); wv[4 * i] = 0.5f * w4[0]; wv[4 * i + 1] = 0.5f * w4[1]; wv[4 * i + 2] = 0.5f * w4[2]; wv[4 * i + 3] = 0.5f * w4[3]; }
;     f32x4 wq[4];
; #pragma unroll
;     for (int i = 0; i < 4; ++i) wq[i] = *(const GAS f32x4*)(Wi + (size_t)(t0 + (tid >> 5)) * 16 + i * 4);
;     bf16x8 kn[2][2];
; #pragma unroll
;     for (int st = 0; st < 2; ++st)
; #pragma unroll
;         for (int ks = 0; ks < 2; ++ks) kn[st][ks] = *(const GAS bf16x8*)(Ki + (size_t)(wid * 32 + 16 * st + q) * 64 + ks * 32 + quad * 8);
;     __syncthreads();
;     {
;         const int qr = tid >> 5, dp = tid & 31;
;         float e0 = 0.f, e1 = 0.f;
; #pragma unroll
;         for (int i = 0; i < 4; ++i) { const f32x4 w4 = wq[i];
; #pragma unroll
;             for (int jj = 0; jj < 4; ++jj) { const unsigned v = *(const LAS unsigned*)(lds + qr * IX_QP + (4 * i + jj) * 128 + dp * 4); e0 += w4[jj] * bflo(v); e1 += w4[jj] * bfhi(v); } }
;         *(LAS unsigned*)(lds + qr * IX_QP + 16 * 128 + dp * 4) = cvt_pk_bf16(0.5f * e0, 0.5f * e1);
;     }
;     __syncthreads();
;     const int niter = (t0 + 16 + 255) >> 8;
;     const int tq = t0 + q;
;     const LAS unsigned char* qrow = lds + q * IX_QP + quad * 16;
;     unsigned thr = 0u;
;     ...
;                 const bf16x8 qa = *(const LAS bf16x8*)(qrow + (hd + 1) * 128), qb2 = *(const LAS bf16x8*)(qrow + (hd + 1) * 128 + 64);
.LBB0_634:
	v_bfe_u32 v48, v59, 4, 2
	s_add_i32 s7, 0, 0x18900
	s_waitcnt vmcnt(7)
	v_mul_f32_e32 v96, 0.5, v32
	v_mad_u32_u24 v32, v73, s72, 0
	s_movk_i32 s10, 0x770
	v_lshl_add_u32 v81, v73, 2, s7
	v_lshl_add_u32 v82, v63, 2, s7
	v_lshl_add_u32 v83, v59, 2, s7
	s_waitcnt vmcnt(4)
	v_mul_f32_e32 v84, 0.5, v44
	v_mul_f32_e32 v85, 0.5, v45
	v_mul_f32_e32 v86, 0.5, v46
	v_mul_f32_e32 v87, 0.5, v47
	v_mul_f32_e32 v88, 0.5, v40
	v_mul_f32_e32 v89, 0.5, v41
	v_mul_f32_e32 v90, 0.5, v42
	v_mul_f32_e32 v91, 0.5, v43
	v_mul_f32_e32 v92, 0.5, v36
	v_mul_f32_e32 v93, 0.5, v37
	v_mul_f32_e32 v94, 0.5, v38
	v_mul_f32_e32 v95, 0.5, v39
	v_mul_f32_e32 v97, 0.5, v33
	v_mul_f32_e32 v98, 0.5, v34
	v_mul_f32_e32 v99, 0.5, v35
	v_lshl_or_b32 v100, v48, 2, s6
	v_cmp_gt_u32_e64 s[6:7], 16, v63
	v_cmp_gt_i32_e64 s[8:9], 16, v59
	s_lshl_b32 s88, s87, 1
	v_mov_b32_e32 v101, 0
	v_mad_u32_u24 v102, v73, s10, v32
	s_mov_b32 s90, 0
	v_add_u32_e32 v103, v32, v154
	ds_read_b128 v[120:123], v103 offset:256
	ds_read_b128 v[124:127], v103 offset:320
	ds_read_b128 v[128:131], v103 offset:384
	ds_read_b128 v[132:135], v103 offset:448
	ds_read_b128 v[136:139], v103 offset:512
	ds_read_b128 v[140:143], v103 offset:576
	ds_read_b128 v[144:147], v103 offset:640
	ds_read_b128 v[148:151], v103 offset:704
	ds_read_b128 v[158:161], v103 offset:768
	ds_read_b128 v[162:165], v103 offset:832
	ds_read_b128 v[166:169], v103 offset:896
	ds_read_b128 v[170:173], v103 offset:960
	s_waitcnt lgkmcnt(0)
	ds_read_b128 v[186:189], v103 offset:1024
	ds_read_b128 v[190:193], v103 offset:1088
	ds_read_b128 v[194:197], v103 offset:1152
	ds_read_b128 v[198:201], v103 offset:1216
	ds_read_b128 v[202:205], v103 offset:1280
	ds_read_b128 v[206:209], v103 offset:1344
	ds_read_b128 v[216:219], v103 offset:1408
	ds_read_b128 v[220:223], v103 offset:1472
	ds_read_b128 v[224:227], v103 offset:1536
	ds_read_b128 v[228:231], v103 offset:1600
	ds_read_b128 v[232:235], v103 offset:1664
	ds_read_b128 v[236:239], v103 offset:1728
	s_waitcnt lgkmcnt(0)
	s_branch .LBB0_636

; #define LAS __attribute__((address_space(3)))
; #define GAS __attribute__((address_space(1)))
; __device__ void indexer_item(LAS unsigned char* lds, const bf16_t* Qi, const bf16_t* Ki, const float* Wi, unsigned* maskout, int qt) {
;     ...
;     for (int it = 0; it < niter; ++it) {
;         const int kb = it * 256 + wid * 32;
;         bf16x8 kf[2][2];
; #pragma unroll
;         for (int st = 0; st < 2; ++st)
; #pragma unroll
;             for (int ks = 0; ks < 2; ++ks) kf[st][ks] = kn[st][ks];
;         { const int itn = (it + 1 < niter) ? it + 1 : it; const int kbn = itn * 256 + wid * 32;
; #pragma unroll
;           for (int st = 0; st < 2; ++st)
; #pragma unroll
;             for (int ks = 0; ks < 2; ++ks) kn[st][ks] = *(const GAS bf16x8*)(Ki + (size_t)(kbn + 16 * st + q) * 64 + ks * 32 + quad * 8); }
;         const f32x4 z4 = {0.f, 0.f, 0.f, 0.f};
;         f32x4 sc0, sc1, c0, c1;
;         { const bf16x8 qa = *(const LAS bf16x8*)(qrow + 16 * 128), qb2 = *(const LAS bf16x8*)(qrow + 16 * 128 + 64);
;           sc0 = __builtin_amdgcn_mfma_f32_16x16x32_bf16(kf[0][0], qa, z4, 0, 0, 0); sc0 = __builtin_amdgcn_mfma_f32_16x16x32_bf16(kf[0][1], qb2, sc0, 0, 0, 0);
;           sc1 = __builtin_amdgcn_mfma_f32_16x16x32_bf16(kf[1][0], qa, z4, 0, 0, 0); sc1 = __builtin_amdgcn_mfma_f32_16x16x32_bf16(kf[1][1], qb2, sc1, 0, 0, 0); }
;         { const bf16x8 qa = *(const LAS bf16x8*)(qrow), qb2 = *(const LAS bf16x8*)(qrow + 64);
;           c0 = __builtin_amdgcn_mfma_f32_16x16x32_bf16(kf[0][0], qa, z4, 0, 0, 0); c0 = __builtin_amdgcn_mfma_f32_16x16x32_bf16(kf[0][1], qb2, c0, 0, 0, 0);
;           c1 = __builtin_amdgcn_mfma_f32_16x16x32_bf16(kf[1][0], qa, z4, 0, 0, 0); c1 = __builtin_amdgcn_mfma_f32_16x16x32_bf16(kf[1][1], qb2, c1, 0, 0, 0); }
; #pragma unroll
;         for (int hd = 0; hd < 16; ++hd) {
;             f32x4 n0 = z4, n1 = z4;
;             if (hd < 15) {
;                 const bf16x8 qa = *(const LAS bf16x8*)(qrow + (hd + 1) * 128), qb2 = *(const LAS bf16x8*)(qrow + (hd + 1) * 128 + 64);
;                 n0 = __builtin_amdgcn_mfma_f32_16x16x32_bf16(kf[0][0], qa, z4, 0, 0, 0); n0 = __builtin_amdgcn_mfma_f32_16x16x32_bf16(kf[0][1], qb2, n0, 0, 0, 0);
;                 n1 = __builtin_amdgcn_mfma_f32_16x16x32_bf16(kf[1][0], qa, z4, 0, 0, 0); n1 = __builtin_amdgcn_mfma_f32_16x16x32_bf16(kf[1][1], qb2, n1, 0, 0, 0);
;             }
;             if (hd < 15)
.LBB0_636:
	s_waitcnt vmcnt(3)
	v_mov_b64_e32 v[42:43], v[30:31]
	s_waitcnt vmcnt(1)
	v_mov_b64_e32 v[50:51], v[22:23]
	v_mov_b64_e32 v[40:41], v[28:29]
	v_mov_b64_e32 v[48:49], v[20:21]
	ds_read_b128 v[28:31], v103 offset:2048
	ds_read_b128 v[32:35], v103 offset:2112
	v_mov_b64_e32 v[46:47], v[18:19]
	s_waitcnt vmcnt(0)
	v_mov_b64_e32 v[54:55], v[26:27]
	v_mov_b64_e32 v[44:45], v[16:17]
	v_mov_b64_e32 v[52:53], v[24:25]
	s_waitcnt lgkmcnt(1)
	v_mfma_f32_16x16x32_bf16 v[36:39], v[40:43], v[28:31], 0
	s_mov_b32 s28, s90
	s_add_i32 s90, s90, 1
	s_cmp_lt_i32 s90, s89
	v_mfma_f32_16x16x32_bf16 v[16:19], v[48:51], v[28:31], 0
	s_cselect_b32 s10, s90, s28
	v_lshl_add_u32 v68, s10, 8, v62
	v_ashrrev_i32_e32 v69, 31, v68
	s_waitcnt lgkmcnt(0)
	v_mfma_f32_16x16x32_bf16 v[36:39], v[44:47], v[32:35], v[36:39]
	v_mfma_f32_16x16x32_bf16 v[32:35], v[52:55], v[32:35], v[16:19]
	s_nop 2
	ds_read_b128 v[16:19], v103
	ds_read_b128 v[20:23], v103 offset:64
	ds_read_b128 v[108:111], v103 offset:192
	s_waitcnt lgkmcnt(2)
	v_mfma_f32_16x16x32_bf16 v[24:27], v[40:43], v[16:19], 0
	s_waitcnt lgkmcnt(1)
	v_mfma_f32_16x16x32_bf16 v[64:67], v[44:47], v[20:23], v[24:27]
	s_nop 5
	ds_read_b128 v[24:27], v103 offset:128
	v_mfma_f32_16x16x32_bf16 v[16:19], v[48:51], v[16:19], 0
	v_mfma_f32_16x16x32_bf16 v[104:107], v[52:55], v[20:23], v[16:19]
	s_waitcnt lgkmcnt(0)
	v_mfma_f32_16x16x32_bf16 v[20:23], v[40:43], v[24:27], 0
	s_nop 4
	v_lshlrev_b64 v[16:17], 7, v[68:69]
	v_lshl_add_u64 v[16:17], v[60:61], 0, v[16:17]
	global_load_dwordx4 v[28:31], v[16:17], off
	s_nop 0
	global_load_dwordx4 v[16:19], v[16:17], off offset:64
	v_mfma_f32_16x16x32_bf16 v[112:115], v[44:47], v[108:111], v[20:23]
	s_nop 2
	v_or_b32_e32 v20, 16, v68
	v_mfma_f32_16x16x32_bf16 v[116:119], v[48:51], v[24:27], 0
	v_ashrrev_i32_e32 v21, 31, v20
	v_lshlrev_b64 v[20:21], 7, v[20:21]
	v_lshl_add_u64 v[24:25], v[60:61], 0, v[20:21]
	v_mov_b32_e32 v68, v35
	global_load_dwordx4 v[20:23], v[24:25], off
	s_nop 0
	global_load_dwordx4 v[24:27], v[24:25], off offset:64
	v_mfma_f32_16x16x32_bf16 v[108:111], v[52:55], v[108:111], v[116:119]
	v_fma_f32 v36, v84, |v64|, v36
	v_fma_f32 v37, v84, |v65|, v37
	v_fma_f32 v38, v84, |v66|, v38
	v_fma_f32 v39, v84, |v67|, v39
	v_fma_f32 v32, v84, |v104|, v32
	v_fma_f32 v33, v84, |v105|, v33
	v_fma_f32 v34, v84, |v106|, v34
	v_fma_f32 v68, v84, |v107|, v68
	ds_read_b128 v[240:243], v103 offset:1792
	ds_read_b128 v[244:247], v103 offset:1856
	ds_read_b128 v[248:251], v103 offset:1920
	ds_read_b128 v[252:255], v103 offset:1984
	v_mfma_f32_16x16x32_bf16 v[116:119], v[40:43], v[120:123], 0
	v_mfma_f32_16x16x32_bf16 v[64:67], v[48:51], v[120:123], 0
	v_mfma_f32_16x16x32_bf16 v[116:119], v[44:47], v[124:127], v[116:119]
	v_mfma_f32_16x16x32_bf16 v[64:67], v[52:55], v[124:127], v[64:67]
	v_fma_f32 v36, v85, |v112|, v36
	v_fma_f32 v37, v85, |v113|, v37
	v_fma_f32 v38, v85, |v114|, v38
	v_fma_f32 v39, v85, |v115|, v39
	v_fma_f32 v32, v85, |v108|, v32
	v_fma_f32 v33, v85, |v109|, v33
	v_fma_f32 v34, v85, |v110|, v34
	v_fma_f32 v68, v85, |v111|, v68
	v_mfma_f32_16x16x32_bf16 v[112:115], v[40:43], v[128:131], 0
	v_mfma_f32_16x16x32_bf16 v[104:107], v[48:51], v[128:131], 0
	v_mfma_f32_16x16x32_bf16 v[112:115], v[44:47], v[132:135], v[112:115]
	v_mfma_f32_16x16x32_bf16 v[104:107], v[52:55], v[132:135], v[104:107]
	v_fma_f32 v36, v86, |v116|, v36
	v_fma_f32 v37, v86, |v117|, v37
	v_fma_f32 v38, v86, |v118|, v38
	v_fma_f32 v39, v86, |v119|, v39
	v_fma_f32 v32, v86, |v64|, v32
	v_fma_f32 v33, v86, |v65|, v33
	v_fma_f32 v34, v86, |v66|, v34
	v_fma_f32 v68, v86, |v67|, v68
	v_mfma_f32_16x16x32_bf16 v[116:119], v[40:43], v[136:139], 0
	v_mfma_f32_16x16x32_bf16 v[64:67], v[48:51], v[136:139], 0
	v_mfma_f32_16x16x32_bf16 v[116:119], v[44:47], v[140:143], v[116:119]
	v_mfma_f32_16x16x32_bf16 v[64:67], v[52:55], v[140:143], v[64:67]
	v_fma_f32 v36, v87, |v112|, v36
	v_fma_f32 v37, v87, |v113|, v37
	v_fma_f32 v38, v87, |v114|, v38
	v_fma_f32 v39, v87, |v115|, v39
	v_fma_f32 v32, v87, |v104|, v32
	v_fma_f32 v33, v87, |v105|, v33
	v_fma_f32 v34, v87, |v106|, v34
	v_fma_f32 v68, v87, |v107|, v68
	v_mfma_f32_16x16x32_bf16 v[112:115], v[40:43], v[144:147], 0
	v_mfma_f32_16x16x32_bf16 v[104:107], v[48:51], v[144:147], 0
	v_mfma_f32_16x16x32_bf16 v[112:115], v[44:47], v[148:151], v[112:115]
	v_mfma_f32_16x16x32_bf16 v[104:107], v[52:55], v[148:151], v[104:107]
	v_fma_f32 v36, v88, |v116|, v36
	v_fma_f32 v37, v88, |v117|, v37
	v_fma_f32 v38, v88, |v118|, v38
	v_fma_f32 v39, v88, |v119|, v39
	v_fma_f32 v32, v88, |v64|, v32
	v_fma_f32 v33, v88, |v65|, v33
	v_fma_f32 v34, v88, |v66|, v34
	v_fma_f32 v68, v88, |v67|, v68
	v_mfma_f32_16x16x32_bf16 v[116:119], v[40:43], v[158:161], 0
	v_mfma_f32_16x16x32_bf16 v[64:67], v[48:51], v[158:161], 0
	v_mfma_f32_16x16x32_bf16 v[116:119], v[44:47], v[162:165], v[116:119]
	v_mfma_f32_16x16x32_bf16 v[64:67], v[52:55], v[162:165], v[64:67]
	v_fma_f32 v36, v89, |v112|, v36
	v_fma_f32 v37, v89, |v113|, v37
	v_fma_f32 v38, v89, |v114|, v38
	v_fma_f32 v39, v89, |v115|, v39
	v_fma_f32 v32, v89, |v104|, v32
	v_fma_f32 v33, v89, |v105|, v33
	v_fma_f32 v34, v89, |v106|, v34
	v_fma_f32 v68, v89, |v107|, v68
	v_mfma_f32_16x16x32_bf16 v[112:115], v[40:43], v[166:169], 0
	v_mfma_f32_16x16x32_bf16 v[104:107], v[48:51], v[166:169], 0
	v_mfma_f32_16x16x32_bf16 v[112:115], v[44:47], v[170:173], v[112:115]
	v_mfma_f32_16x16x32_bf16 v[104:107], v[52:55], v[170:173], v[104:107]
	v_fma_f32 v36, v90, |v116|, v36
	v_fma_f32 v37, v90, |v117|, v37
	v_fma_f32 v38, v90, |v118|, v38
	v_fma_f32 v39, v90, |v119|, v39
	v_fma_f32 v32, v90, |v64|, v32
	v_fma_f32 v33, v90, |v65|, v33
	v_fma_f32 v34, v90, |v66|, v34
; __device__ void indexer_item(LAS unsigned char* lds, const bf16_t* Qi, const bf16_t* Ki, const float* Wi, unsigned* maskout, int qt) {
;     ...
; #pragma unroll
;         for (int hd = 0; hd < 16; ++hd) {
;             f32x4 n0 = z4, n1 = z4;
;             if (hd < 15) {
;                 const bf16x8 qa = *(const LAS bf16x8*)(qrow + (hd + 1) * 128), qb2 = *(const LAS bf16x8*)(qrow + (hd + 1) * 128 + 64);
;                 n0 = __builtin_amdgcn_mfma_f32_16x16x32_bf16(kf[0][0], qa, z4, 0, 0, 0); n0 = __builtin_amdgcn_mfma_f32_16x16x32_bf16(kf[0][1], qb2, n0, 0, 0, 0);
;                 n1 = __builtin_amdgcn_mfma_f32_16x16x32_bf16(kf[1][0], qa, z4, 0, 0, 0); n1 = __builtin_amdgcn_mfma_f32_16x16x32_bf16(kf[1][1], qb2, n1, 0, 0, 0);
;             }
;             if (hd < 15)
;                 asm volatile("v_fma_f32 %0, %16, |%8|, %0\n\tv_fma_f32 %1, %16, |%9|, %1\n\tv_fma_f32 %2, %16, |%10|, %2\n\tv_fma_f32 %3, %16, |%11|, %3\n\t"
;                              "v_fma_f32 %4, %16, |%12|, %4\n\tv_fma_f32 %5, %16, |%13|, %5\n\tv_fma_f32 %6, %16, |%14|, %6\n\tv_fma_f32 %7, %16, |%15|, %7"
;                              : "+v"(sc0[0]), "+v"(sc0[1]), "+v"(sc0[2]), "+v"(sc0[3]), "+v"(sc1[0]), "+v"(sc1[1]), "+v"(sc1[2]), "+v"(sc1[3])
;                              : "v"(c0[0]), "v"(c0[1]), "v"(c0[2]), "v"(c0[3]), "v"(c1[0]), "v"(c1[1]), "v"(c1[2]), "v"(c1[3]), "v"(wv[hd]), "v"(n0), "v"(n1));
;             else
;                 asm volatile("s_nop 15\n\ts_nop 15\n\t"
;                              "v_fma_f32 %0, %16, |%8|, %0\n\tv_fma_f32 %1, %16, |%9|, %1\n\tv_fma_f32 %2, %16, |%10|, %2\n\tv_fma_f32 %3, %16, |%11|, %3\n\t"
;                              "v_fma_f32 %4, %16, |%12|, %4\n\tv_fma_f32 %5, %16, |%13|, %5\n\tv_fma_f32 %6, %16, |%14|, %6\n\tv_fma_f32 %7, %16, |%15|, %7"
;                              : "+v"(sc0[0]), "+v"(sc0[1]), "+v"(sc0[2]), "+v"(sc0[3]), "+v"(sc1[0]), "+v"(sc1[1]), "+v"(sc1[2]), "+v"(sc1[3])
;                              : "v"(c0[0]), "v"(c0[1]), "v"(c0[2]), "v"(c0[3]), "v"(c1[0]), "v"(c1[1]), "v"(c1[2]), "v"(c1[3]), "v"(wv[hd]));
;             c0 = n0; c1 = n1;
;         }
;         unsigned k32[8]; int keyi[8];
; #pragma unroll
;         for (int j = 0; j < 4; ++j) { k32[j] = f2key(sc0[j]); k32[4 + j] = f2key(sc1[j]); keyi[j] = kb + quad * 4 + j; keyi[4 + j] = kb + 16 + quad * 4 + j; }
;         int np = 0;
; #pragma unroll
	v_fma_f32 v68, v90, |v67|, v68
	v_mfma_f32_16x16x32_bf16 v[116:119], v[40:43], v[186:189], 0
	v_mfma_f32_16x16x32_bf16 v[64:67], v[48:51], v[186:189], 0
	v_mfma_f32_16x16x32_bf16 v[116:119], v[44:47], v[190:193], v[116:119]
	v_mfma_f32_16x16x32_bf16 v[64:67], v[52:55], v[190:193], v[64:67]
	v_fma_f32 v36, v91, |v112|, v36
	v_fma_f32 v37, v91, |v113|, v37
	v_fma_f32 v38, v91, |v114|, v38
	v_fma_f32 v39, v91, |v115|, v39
	v_fma_f32 v32, v91, |v104|, v32
	v_fma_f32 v33, v91, |v105|, v33
	v_fma_f32 v34, v91, |v106|, v34
	v_fma_f32 v68, v91, |v107|, v68
	v_mfma_f32_16x16x32_bf16 v[112:115], v[40:43], v[194:197], 0
	v_mfma_f32_16x16x32_bf16 v[104:107], v[48:51], v[194:197], 0
	v_mfma_f32_16x16x32_bf16 v[112:115], v[44:47], v[198:201], v[112:115]
	v_mfma_f32_16x16x32_bf16 v[104:107], v[52:55], v[198:201], v[104:107]
	v_fma_f32 v36, v92, |v116|, v36
	v_fma_f32 v37, v92, |v117|, v37
	v_fma_f32 v38, v92, |v118|, v38
	v_fma_f32 v39, v92, |v119|, v39
	v_fma_f32 v32, v92, |v64|, v32
	v_fma_f32 v33, v92, |v65|, v33
	v_fma_f32 v34, v92, |v66|, v34
	v_fma_f32 v68, v92, |v67|, v68
	v_mfma_f32_16x16x32_bf16 v[116:119], v[40:43], v[202:205], 0
	v_mfma_f32_16x16x32_bf16 v[64:67], v[48:51], v[202:205], 0
	v_mfma_f32_16x16x32_bf16 v[116:119], v[44:47], v[206:209], v[116:119]
	v_mfma_f32_16x16x32_bf16 v[64:67], v[52:55], v[206:209], v[64:67]
	v_fma_f32 v36, v93, |v112|, v36
	v_fma_f32 v37, v93, |v113|, v37
	v_fma_f32 v38, v93, |v114|, v38
	v_fma_f32 v39, v93, |v115|, v39
	v_fma_f32 v32, v93, |v104|, v32
	v_fma_f32 v33, v93, |v105|, v33
	v_fma_f32 v34, v93, |v106|, v34
	v_fma_f32 v68, v93, |v107|, v68
	v_mfma_f32_16x16x32_bf16 v[112:115], v[40:43], v[216:219], 0
	v_mfma_f32_16x16x32_bf16 v[104:107], v[48:51], v[216:219], 0
	v_mfma_f32_16x16x32_bf16 v[112:115], v[44:47], v[220:223], v[112:115]
	v_mfma_f32_16x16x32_bf16 v[104:107], v[52:55], v[220:223], v[104:107]
	v_fma_f32 v36, v94, |v116|, v36
	v_fma_f32 v37, v94, |v117|, v37
	v_fma_f32 v38, v94, |v118|, v38
	v_fma_f32 v39, v94, |v119|, v39
	v_fma_f32 v32, v94, |v64|, v32
	v_fma_f32 v33, v94, |v65|, v33
	v_fma_f32 v34, v94, |v66|, v34
	v_fma_f32 v68, v94, |v67|, v68
	v_mfma_f32_16x16x32_bf16 v[116:119], v[40:43], v[224:227], 0
	v_mfma_f32_16x16x32_bf16 v[64:67], v[48:51], v[224:227], 0
	v_mfma_f32_16x16x32_bf16 v[116:119], v[44:47], v[228:231], v[116:119]
	v_mfma_f32_16x16x32_bf16 v[64:67], v[52:55], v[228:231], v[64:67]
	v_fma_f32 v36, v95, |v112|, v36
	v_fma_f32 v37, v95, |v113|, v37
	v_fma_f32 v38, v95, |v114|, v38
	v_fma_f32 v39, v95, |v115|, v39
	v_fma_f32 v32, v95, |v104|, v32
	v_fma_f32 v33, v95, |v105|, v33
	v_fma_f32 v34, v95, |v106|, v34
	v_fma_f32 v68, v95, |v107|, v68
	v_mfma_f32_16x16x32_bf16 v[112:115], v[40:43], v[232:235], 0
	v_mfma_f32_16x16x32_bf16 v[104:107], v[48:51], v[232:235], 0
	v_mfma_f32_16x16x32_bf16 v[112:115], v[44:47], v[236:239], v[112:115]
	v_mfma_f32_16x16x32_bf16 v[104:107], v[52:55], v[236:239], v[104:107]
	v_fma_f32 v36, v96, |v116|, v36
	v_fma_f32 v37, v96, |v117|, v37
	v_fma_f32 v38, v96, |v118|, v38
	v_fma_f32 v39, v96, |v119|, v39
	v_fma_f32 v32, v96, |v64|, v32
	v_fma_f32 v33, v96, |v65|, v33
	v_fma_f32 v34, v96, |v66|, v34
	v_fma_f32 v68, v96, |v67|, v68
	s_waitcnt lgkmcnt(3)
	v_mfma_f32_16x16x32_bf16 v[116:119], v[40:43], v[240:243], 0
	v_mfma_f32_16x16x32_bf16 v[64:67], v[48:51], v[240:243], 0
	s_waitcnt lgkmcnt(2)
	v_mfma_f32_16x16x32_bf16 v[116:119], v[44:47], v[244:247], v[116:119]
	v_mfma_f32_16x16x32_bf16 v[64:67], v[52:55], v[244:247], v[64:67]
	v_fma_f32 v36, v97, |v112|, v36
	v_fma_f32 v37, v97, |v113|, v37
	v_fma_f32 v38, v97, |v114|, v38
	v_fma_f32 v39, v97, |v115|, v39
	v_fma_f32 v32, v97, |v104|, v32
	v_fma_f32 v33, v97, |v105|, v33
	v_fma_f32 v34, v97, |v106|, v34
	v_fma_f32 v68, v97, |v107|, v68
	s_waitcnt lgkmcnt(1)
	v_mfma_f32_16x16x32_bf16 v[40:43], v[40:43], v[248:251], 0
	s_waitcnt lgkmcnt(0)
	v_mfma_f32_16x16x32_bf16 v[40:43], v[44:47], v[252:255], v[40:43]
	v_mfma_f32_16x16x32_bf16 v[44:47], v[48:51], v[248:251], 0
	v_mfma_f32_16x16x32_bf16 v[44:47], v[52:55], v[252:255], v[44:47]
	v_fma_f32 v36, v98, |v116|, v36
	v_fma_f32 v37, v98, |v117|, v37
	v_fma_f32 v38, v98, |v118|, v38
	v_fma_f32 v39, v98, |v119|, v39
	v_fma_f32 v32, v98, |v64|, v32
	v_fma_f32 v33, v98, |v65|, v33
	v_fma_f32 v34, v98, |v66|, v34
	v_fma_f32 v68, v98, |v67|, v68
	s_nop 0
	s_nop 15
	s_nop 15
	v_fma_f32 v36, v99, |v40|, v36
	v_fma_f32 v37, v99, |v41|, v37
	v_fma_f32 v38, v99, |v42|, v38
	v_fma_f32 v39, v99, |v43|, v39
	v_fma_f32 v32, v99, |v44|, v32
	v_fma_f32 v33, v99, |v45|, v33
	v_fma_f32 v34, v99, |v46|, v34
	v_fma_f32 v68, v99, |v47|, v68
	s_nop 4
	v_lshl_add_u32 v43, s28, 8, v100
	v_ashrrev_i32_e32 v45, 31, v36
	v_ashrrev_i32_e32 v46, 31, v37
	v_or_b32_e32 v45, 0x80000000, v45
	v_or_b32_e32 v46, 0x80000000, v46
	v_xor_b32_e32 v154, v45, v36
	v_xor_b32_e32 v44, v46, v37
	v_ashrrev_i32_e32 v45, 31, v38
	v_ashrrev_i32_e32 v46, 31, v39
	v_or_b32_e32 v45, 0x80000000, v45
	v_or_b32_e32 v46, 0x80000000, v46
	v_xor_b32_e32 v42, v45, v38
	v_xor_b32_e32 v40, v46, v39
	v_ashrrev_i32_e32 v45, 31, v32
	v_ashrrev_i32_e32 v46, 31, v33
	v_or_b32_e32 v45, 0x80000000, v45
	v_or_b32_e32 v46, 0x80000000, v46
	v_xor_b32_e32 v38, v45, v32
	v_xor_b32_e32 v36, v46, v33
	v_ashrrev_i32_e32 v45, 31, v34
	v_ashrrev_i32_e32 v46, 31, v68
	v_or_b32_e32 v45, 0x80000000, v45
	v_or_b32_e32 v46, 0x80000000, v46
	v_xor_b32_e32 v34, v45, v34
	v_xor_b32_e32 v32, v46, v68
	v_or_b32_e32 v41, 2, v43
	v_or_b32_e32 v107, 3, v43
	v_or_b32_e32 v106, 16, v43
	v_or_b32_e32 v35, 17, v43
	v_or_b32_e32 v105, 18, v43
	v_or_b32_e32 v104, 19, v43
	v_cmp_le_i32_e64 s[24:25], v43, v56
	v_cmp_lt_i32_e64 s[22:23], v43, v56
	v_cmp_le_i32_e64 s[20:21], v41, v56
	v_cmp_le_i32_e64 s[18:19], v107, v56
	v_cmp_le_i32_e64 s[16:17], v106, v56
	v_cmp_le_i32_e64 s[14:15], v35, v56
	v_cmp_le_i32_e64 s[12:13], v105, v56
	v_cmp_gt_u32_e64 s[10:11], v154, v101
	v_cmp_gt_u32_e32 vcc, v44, v101
	s_and_b64 s[10:11], s[24:25], s[10:11]
	v_cndmask_b32_e64 v45, 0, 1, s[10:11]
	s_and_b64 vcc, s[22:23], vcc
	v_addc_co_u32_e32 v45, vcc, 0, v45, vcc
	v_cmp_gt_u32_e64 s[10:11], v42, v101
	v_cmp_gt_u32_e32 vcc, v40, v101
	s_and_b64 s[10:11], s[20:21], s[10:11]
	v_cndmask_b32_e64 v46, 0, 1, s[10:11]
	s_and_b64 vcc, s[18:19], vcc
	v_addc_co_u32_e32 v45, vcc, v45, v46, vcc
	v_cmp_gt_u32_e64 s[10:11], v38, v101
	v_cmp_gt_u32_e32 vcc, v36, v101
	s_and_b64 s[10:11], s[16:17], s[10:11]
	v_cndmask_b32_e64 v46, 0, 1, s[10:11]
	s_and_b64 vcc, s[14:15], vcc
	v_addc_co_u32_e32 v45, vcc, v45, v46, vcc
	v_cmp_le_i32_e64 s[10:11], v104, v56
	v_cmp_gt_u32_e64 s[26:27], v34, v101
	v_cmp_gt_u32_e32 vcc, v32, v101
	s_and_b64 s[26:27], s[12:13], s[26:27]
	v_cndmask_b32_e64 v46, 0, 1, s[26:27]
	s_and_b64 vcc, s[10:11], vcc
	v_addc_co_u32_e32 v33, vcc, v45, v46, vcc
	s_bitcmp0_b32 s28, 0
	s_cselect_b32 s30, 16, 48
	v_cmp_ne_u32_e32 vcc, 0, v33
	s_and_saveexec_b64 s[26:27], vcc
	v_lshl_add_u32 v37, s30, 2, v81
	ds_add_u32 v37, v33
	s_or_b64 exec, exec, s[26:27]
	s_waitcnt lgkmcnt(0)
	s_barrier
; __device__ void indexer_item(LAS unsigned char* lds, const bf16_t* Qi, const bf16_t* Ki, const float* Wi, unsigned* maskout, int qt) {
;     ...
;         bool round;
;         {
;             const unsigned both = (lane < 16) ? cnt[lane] + cnt[cnoff + lane] : 0u;
;             if (tid < 16) cnt[(cnoff ^ 32) + tid] = 0u;
;             round = __ballot(both > 512u) != 0ull;
;             if (round) {
	s_mov_b64 s[26:27], 0
	s_and_saveexec_b64 s[28:29], s[6:7]
	s_cbranch_execz .LBB0_640
	v_lshl_add_u32 v33, s30, 2, v82
	ds_read_b32 v37, v82
	ds_read_b32 v33, v33
	s_waitcnt lgkmcnt(0)
	v_add_u32_e32 v33, v33, v37
	v_cmp_lt_u32_e32 vcc, s73, v33
	s_and_b64 s[26:27], vcc, exec
